# static s_setprio 1 for waves 4-7 kept for the rest of the kernel (no reset at the GEMM loop exits)
# baseline (speedup 1.0000x reference)
.Lsp_done_1:
.LBB0_437:
	s_add_u32 s14, s12, 0xfffc0080
	s_addc_u32 s15, s13, -1
	s_add_i32 s28, 0, 0x10000
	s_cmp_eq_u32 s27, 12
	s_cselect_b32 s17, s3, s15
	s_cselect_b32 s16, s11, s14
	v_add_u32_e32 v152, s28, v190
	s_cselect_b32 s15, s9, s24
	s_cselect_b32 s14, s22, s23
	s_add_i32 s31, 0, 0x14000
	ds_read_b128 v[132:135], v152
	ds_read_b128 v[136:139], v152 offset:1024
	ds_read_b128 v[160:163], v152 offset:2048
	ds_read_b128 v[164:167], v152 offset:3072
	v_add_u32_e32 v152, s31, v190
	ds_read_b128 v[168:171], v152
	ds_read_b128 v[172:175], v152 offset:1024
	ds_read_b128 v[196:199], v152 offset:2048
	ds_read_b128 v[200:203], v152 offset:3072
	v_lshl_add_u64 v[152:153], s[12:13], 0, v[158:159]
	s_add_i32 m0, s51, 0xc000
	ds_read_b128 v[204:207], v194
	ds_read_b128 v[208:211], v194 offset:1024
	ds_read_b128 v[212:215], v194 offset:2048
	ds_read_b128 v[216:219], v194 offset:3072
	ds_read_b128 v[220:223], v194 offset:4096
	ds_read_b128 v[224:227], v194 offset:5120
	ds_read_b128 v[228:231], v194 offset:6144
	ds_read_b128 v[232:235], v194 offset:7168
	global_load_lds_dwordx4 v[152:153], off
	v_lshl_add_u64 v[152:153], s[12:13], 0, v[146:147]
	s_add_i32 m0, s51, 0xe000
	s_nop 0
	global_load_lds_dwordx4 v[152:153], off
	s_waitcnt vmcnt(8)
	s_waitcnt lgkmcnt(0)
	s_barrier
	s_waitcnt lgkmcnt(0)
	v_mfma_f32_16x16x32_bf16 v[128:131], v[132:135], v[204:207], v[128:131]
	v_mfma_f32_16x16x32_bf16 v[124:127], v[160:163], v[204:207], v[124:127]
	v_mfma_f32_16x16x32_bf16 v[112:115], v[132:135], v[212:215], v[112:115]
	v_mfma_f32_16x16x32_bf16 v[108:111], v[160:163], v[212:215], v[108:111]
	v_mfma_f32_16x16x32_bf16 v[96:99], v[132:135], v[220:223], v[96:99]
	v_mfma_f32_16x16x32_bf16 v[92:95], v[160:163], v[220:223], v[92:95]
	v_mfma_f32_16x16x32_bf16 v[80:83], v[132:135], v[228:231], v[80:83]
	v_mfma_f32_16x16x32_bf16 v[76:79], v[160:163], v[228:231], v[76:79]
	v_mfma_f32_16x16x32_bf16 v[128:131], v[136:139], v[208:211], v[128:131]
	v_mfma_f32_16x16x32_bf16 v[124:127], v[164:167], v[208:211], v[124:127]
	v_mfma_f32_16x16x32_bf16 v[112:115], v[136:139], v[216:219], v[112:115]
	v_mfma_f32_16x16x32_bf16 v[108:111], v[164:167], v[216:219], v[108:111]
	v_mfma_f32_16x16x32_bf16 v[96:99], v[136:139], v[224:227], v[96:99]
	v_mfma_f32_16x16x32_bf16 v[92:95], v[164:167], v[224:227], v[92:95]
	v_mfma_f32_16x16x32_bf16 v[80:83], v[136:139], v[232:235], v[80:83]
	v_mfma_f32_16x16x32_bf16 v[76:79], v[164:167], v[232:235], v[76:79]
	v_mfma_f32_16x16x32_bf16 v[120:123], v[168:171], v[204:207], v[120:123]
	v_mfma_f32_16x16x32_bf16 v[116:119], v[196:199], v[204:207], v[116:119]
	v_mfma_f32_16x16x32_bf16 v[104:107], v[168:171], v[212:215], v[104:107]
	v_mfma_f32_16x16x32_bf16 v[100:103], v[196:199], v[212:215], v[100:103]
	v_mfma_f32_16x16x32_bf16 v[88:91], v[168:171], v[220:223], v[88:91]
	v_mfma_f32_16x16x32_bf16 v[84:87], v[196:199], v[220:223], v[84:87]
	v_mfma_f32_16x16x32_bf16 v[72:75], v[168:171], v[228:231], v[72:75]
	v_mfma_f32_16x16x32_bf16 v[68:71], v[196:199], v[228:231], v[68:71]
	v_mfma_f32_16x16x32_bf16 v[120:123], v[172:175], v[208:211], v[120:123]
	v_mfma_f32_16x16x32_bf16 v[116:119], v[200:203], v[208:211], v[116:119]
	v_mfma_f32_16x16x32_bf16 v[104:107], v[172:175], v[216:219], v[104:107]
	v_mfma_f32_16x16x32_bf16 v[100:103], v[200:203], v[216:219], v[100:103]
	v_mfma_f32_16x16x32_bf16 v[88:91], v[172:175], v[224:227], v[88:91]
	v_mfma_f32_16x16x32_bf16 v[84:87], v[200:203], v[224:227], v[84:87]
	v_mfma_f32_16x16x32_bf16 v[72:75], v[172:175], v[232:235], v[72:75]
	v_mfma_f32_16x16x32_bf16 v[68:71], v[200:203], v[232:235], v[68:71]
	s_barrier
	s_add_i32 s28, s28, s58
	v_lshl_add_u64 v[152:153], s[14:15], 0, v[140:141]
	s_mov_b32 m0, s28
	ds_read_b128 v[204:207], v194 offset:16384
	ds_read_b128 v[208:211], v194 offset:17408
	ds_read_b128 v[212:215], v194 offset:18432
	ds_read_b128 v[216:219], v194 offset:19456
	ds_read_b128 v[220:223], v194 offset:20480
	ds_read_b128 v[224:227], v194 offset:21504
	ds_read_b128 v[228:231], v194 offset:22528
	ds_read_b128 v[232:235], v194 offset:23552
	global_load_lds_dwordx4 v[152:153], off
	s_add_i32 m0, s28, 0x2000
	s_add_u32 s36, s14, 0x40000
	v_lshl_add_u64 v[236:237], s[14:15], 0, v[144:145]
	s_addc_u32 s37, s15, 0
	s_add_i32 s28, s31, s58
	global_load_lds_dwordx4 v[236:237], off
	v_lshl_add_u64 v[238:239], s[36:37], 0, v[140:141]
	s_mov_b32 m0, s28
	v_lshl_add_u64 v[240:241], s[16:17], 0, v[142:143]
	global_load_lds_dwordx4 v[238:239], off
	v_lshl_add_u64 v[238:239], s[36:37], 0, v[144:145]
	s_add_i32 m0, s28, 0x2000
	s_nop 0
	global_load_lds_dwordx4 v[238:239], off
	v_lshl_add_u64 v[238:239], s[16:17], 0, v[0:1]
	s_mov_b32 m0, s51
	s_nop 0
	global_load_lds_dwordx4 v[238:239], off
	s_mov_b32 m0, s59
	s_nop 0
	global_load_lds_dwordx4 v[240:241], off
	s_waitcnt vmcnt(8)
	s_waitcnt lgkmcnt(0)
	s_barrier
	s_waitcnt lgkmcnt(0)
	v_mfma_f32_16x16x32_bf16 v[64:67], v[132:135], v[204:207], v[64:67]
	v_mfma_f32_16x16x32_bf16 v[60:63], v[160:163], v[204:207], v[60:63]
	v_mfma_f32_16x16x32_bf16 v[48:51], v[132:135], v[212:215], v[48:51]
	v_mfma_f32_16x16x32_bf16 v[44:47], v[160:163], v[212:215], v[44:47]
	v_mfma_f32_16x16x32_bf16 v[32:35], v[132:135], v[220:223], v[32:35]
	v_mfma_f32_16x16x32_bf16 v[28:31], v[160:163], v[220:223], v[28:31]
	v_mfma_f32_16x16x32_bf16 v[16:19], v[132:135], v[228:231], v[16:19]
	v_mfma_f32_16x16x32_bf16 v[12:15], v[160:163], v[228:231], v[12:15]
	v_mfma_f32_16x16x32_bf16 v[64:67], v[136:139], v[208:211], v[64:67]
	v_mfma_f32_16x16x32_bf16 v[60:63], v[164:167], v[208:211], v[60:63]
	v_mfma_f32_16x16x32_bf16 v[48:51], v[136:139], v[216:219], v[48:51]
	v_mfma_f32_16x16x32_bf16 v[44:47], v[164:167], v[216:219], v[44:47]
	v_mfma_f32_16x16x32_bf16 v[32:35], v[136:139], v[224:227], v[32:35]
	v_mfma_f32_16x16x32_bf16 v[28:31], v[164:167], v[224:227], v[28:31]
	v_mfma_f32_16x16x32_bf16 v[16:19], v[136:139], v[232:235], v[16:19]
	v_mfma_f32_16x16x32_bf16 v[12:15], v[164:167], v[232:235], v[12:15]
	v_mfma_f32_16x16x32_bf16 v[56:59], v[168:171], v[204:207], v[56:59]
	v_mfma_f32_16x16x32_bf16 v[52:55], v[196:199], v[204:207], v[52:55]
	v_mfma_f32_16x16x32_bf16 v[40:43], v[168:171], v[212:215], v[40:43]
	v_mfma_f32_16x16x32_bf16 v[36:39], v[196:199], v[212:215], v[36:39]
	v_mfma_f32_16x16x32_bf16 v[24:27], v[168:171], v[220:223], v[24:27]
	v_mfma_f32_16x16x32_bf16 v[20:23], v[196:199], v[220:223], v[20:23]
	v_mfma_f32_16x16x32_bf16 v[8:11], v[168:171], v[228:231], v[8:11]
	v_mfma_f32_16x16x32_bf16 v[4:7], v[196:199], v[228:231], v[4:7]
	v_mfma_f32_16x16x32_bf16 v[56:59], v[172:175], v[208:211], v[56:59]
	v_mfma_f32_16x16x32_bf16 v[52:55], v[200:203], v[208:211], v[52:55]
	v_mfma_f32_16x16x32_bf16 v[40:43], v[172:175], v[216:219], v[40:43]
	v_mfma_f32_16x16x32_bf16 v[36:39], v[200:203], v[216:219], v[36:39]
	v_mfma_f32_16x16x32_bf16 v[24:27], v[172:175], v[224:227], v[24:27]
	v_mfma_f32_16x16x32_bf16 v[20:23], v[200:203], v[224:227], v[20:23]
	v_mfma_f32_16x16x32_bf16 v[8:11], v[172:175], v[232:235], v[8:11]
	v_mfma_f32_16x16x32_bf16 v[4:7], v[200:203], v[232:235], v[4:7]
	s_barrier
	s_add_i32 s28, 0, 0x18000
	s_add_i32 s31, 0, 0x1c000
	v_add_u32_e32 v164, s28, v190
	v_add_u32_e32 v195, s31, v190
	ds_read_b128 v[132:135], v164
	ds_read_b128 v[136:139], v164 offset:1024
	ds_read_b128 v[160:163], v164 offset:2048
	ds_read_b128 v[164:167], v164 offset:3072
	ds_read_b128 v[168:171], v195
	ds_read_b128 v[172:175], v195 offset:1024
	ds_read_b128 v[196:199], v195 offset:2048
	ds_read_b128 v[200:203], v195 offset:3072
	s_add_u32 s16, s16, 0x40000
	s_addc_u32 s17, s17, 0
	s_mov_b32 m0, s52
	v_lshl_add_u64 v[242:243], s[16:17], 0, v[0:1]
	ds_read_b128 v[204:207], v194 offset:32768
	ds_read_b128 v[208:211], v194 offset:33792
	ds_read_b128 v[212:215], v194 offset:34816
	ds_read_b128 v[216:219], v194 offset:35840
	ds_read_b128 v[220:223], v194 offset:36864
	ds_read_b128 v[224:227], v194 offset:37888
	ds_read_b128 v[228:231], v194 offset:38912
	ds_read_b128 v[232:235], v194 offset:39936
	global_load_lds_dwordx4 v[242:243], off
	v_lshl_add_u64 v[242:243], s[16:17], 0, v[142:143]
	s_mov_b32 m0, s71
	s_nop 0
	global_load_lds_dwordx4 v[242:243], off
	s_waitcnt vmcnt(8)
	s_waitcnt lgkmcnt(0)
	s_barrier
	s_waitcnt lgkmcnt(0)
	v_mfma_f32_16x16x32_bf16 v[128:131], v[132:135], v[204:207], v[128:131]
	v_mfma_f32_16x16x32_bf16 v[124:127], v[160:163], v[204:207], v[124:127]
	v_mfma_f32_16x16x32_bf16 v[112:115], v[132:135], v[212:215], v[112:115]
	v_mfma_f32_16x16x32_bf16 v[108:111], v[160:163], v[212:215], v[108:111]
	v_mfma_f32_16x16x32_bf16 v[96:99], v[132:135], v[220:223], v[96:99]
	v_mfma_f32_16x16x32_bf16 v[92:95], v[160:163], v[220:223], v[92:95]
	v_mfma_f32_16x16x32_bf16 v[80:83], v[132:135], v[228:231], v[80:83]
	v_mfma_f32_16x16x32_bf16 v[76:79], v[160:163], v[228:231], v[76:79]
	v_mfma_f32_16x16x32_bf16 v[128:131], v[136:139], v[208:211], v[128:131]
	v_mfma_f32_16x16x32_bf16 v[124:127], v[164:167], v[208:211], v[124:127]
	v_mfma_f32_16x16x32_bf16 v[112:115], v[136:139], v[216:219], v[112:115]
	v_mfma_f32_16x16x32_bf16 v[108:111], v[164:167], v[216:219], v[108:111]
	v_mfma_f32_16x16x32_bf16 v[96:99], v[136:139], v[224:227], v[96:99]
	v_mfma_f32_16x16x32_bf16 v[92:95], v[164:167], v[224:227], v[92:95]
	v_mfma_f32_16x16x32_bf16 v[80:83], v[136:139], v[232:235], v[80:83]
	v_mfma_f32_16x16x32_bf16 v[76:79], v[164:167], v[232:235], v[76:79]
	v_mfma_f32_16x16x32_bf16 v[120:123], v[168:171], v[204:207], v[120:123]
	v_mfma_f32_16x16x32_bf16 v[116:119], v[196:199], v[204:207], v[116:119]
	v_mfma_f32_16x16x32_bf16 v[104:107], v[168:171], v[212:215], v[104:107]
	v_mfma_f32_16x16x32_bf16 v[100:103], v[196:199], v[212:215], v[100:103]
	v_mfma_f32_16x16x32_bf16 v[88:91], v[168:171], v[220:223], v[88:91]
	v_mfma_f32_16x16x32_bf16 v[84:87], v[196:199], v[220:223], v[84:87]
	v_mfma_f32_16x16x32_bf16 v[72:75], v[168:171], v[228:231], v[72:75]
	v_mfma_f32_16x16x32_bf16 v[68:71], v[196:199], v[228:231], v[68:71]
	v_mfma_f32_16x16x32_bf16 v[120:123], v[172:175], v[208:211], v[120:123]
	v_mfma_f32_16x16x32_bf16 v[116:119], v[200:203], v[208:211], v[116:119]
	v_mfma_f32_16x16x32_bf16 v[104:107], v[172:175], v[216:219], v[104:107]
	v_mfma_f32_16x16x32_bf16 v[100:103], v[200:203], v[216:219], v[100:103]
	v_mfma_f32_16x16x32_bf16 v[88:91], v[172:175], v[224:227], v[88:91]
	v_mfma_f32_16x16x32_bf16 v[84:87], v[200:203], v[224:227], v[84:87]
	v_mfma_f32_16x16x32_bf16 v[72:75], v[172:175], v[232:235], v[72:75]
	v_mfma_f32_16x16x32_bf16 v[68:71], v[200:203], v[232:235], v[68:71]
	s_barrier
	s_add_i32 s16, s28, s58
	v_lshl_add_u64 v[152:153], v[152:153], 0, s[84:85]
	s_mov_b32 m0, s16
	ds_read_b128 v[204:207], v194 offset:49152
	ds_read_b128 v[208:211], v194 offset:50176
	ds_read_b128 v[212:215], v194 offset:51200
	ds_read_b128 v[216:219], v194 offset:52224
	ds_read_b128 v[220:223], v194 offset:53248
	ds_read_b128 v[224:227], v194 offset:54272
	ds_read_b128 v[228:231], v194 offset:55296
	ds_read_b128 v[232:235], v194 offset:56320
	global_load_lds_dwordx4 v[152:153], off
	s_add_i32 m0, s16, 0x2000
	s_add_u32 s14, s14, 0x40080
	v_lshl_add_u64 v[152:153], v[236:237], 0, s[84:85]
	s_addc_u32 s15, s15, 0
	s_add_i32 s16, s31, s58
	global_load_lds_dwordx4 v[152:153], off
	v_lshl_add_u64 v[152:153], s[14:15], 0, v[140:141]
	s_mov_b32 m0, s16
	s_nop 0
	global_load_lds_dwordx4 v[152:153], off
	v_lshl_add_u64 v[152:153], s[14:15], 0, v[144:145]
	s_add_i32 m0, s16, 0x2000
	s_nop 0
	global_load_lds_dwordx4 v[152:153], off
	v_lshl_add_u64 v[152:153], v[238:239], 0, s[84:85]
	s_mov_b32 m0, s18
	s_nop 0
	global_load_lds_dwordx4 v[152:153], off
	v_lshl_add_u64 v[152:153], v[240:241], 0, s[84:85]
	s_mov_b32 m0, s46
	s_nop 0
	global_load_lds_dwordx4 v[152:153], off
	s_waitcnt vmcnt(8)
	s_waitcnt lgkmcnt(0)
	s_barrier
	s_waitcnt lgkmcnt(0)
	v_mfma_f32_16x16x32_bf16 v[64:67], v[132:135], v[204:207], v[64:67]
	v_mfma_f32_16x16x32_bf16 v[60:63], v[160:163], v[204:207], v[60:63]
	v_mfma_f32_16x16x32_bf16 v[48:51], v[132:135], v[212:215], v[48:51]
	v_mfma_f32_16x16x32_bf16 v[44:47], v[160:163], v[212:215], v[44:47]
	v_mfma_f32_16x16x32_bf16 v[32:35], v[132:135], v[220:223], v[32:35]
	v_mfma_f32_16x16x32_bf16 v[28:31], v[160:163], v[220:223], v[28:31]
	v_mfma_f32_16x16x32_bf16 v[16:19], v[132:135], v[228:231], v[16:19]
	v_mfma_f32_16x16x32_bf16 v[12:15], v[160:163], v[228:231], v[12:15]
	v_mfma_f32_16x16x32_bf16 v[64:67], v[136:139], v[208:211], v[64:67]
	v_mfma_f32_16x16x32_bf16 v[60:63], v[164:167], v[208:211], v[60:63]
	v_mfma_f32_16x16x32_bf16 v[48:51], v[136:139], v[216:219], v[48:51]
	v_mfma_f32_16x16x32_bf16 v[44:47], v[164:167], v[216:219], v[44:47]
	v_mfma_f32_16x16x32_bf16 v[32:35], v[136:139], v[224:227], v[32:35]
	v_mfma_f32_16x16x32_bf16 v[28:31], v[164:167], v[224:227], v[28:31]
	v_mfma_f32_16x16x32_bf16 v[16:19], v[136:139], v[232:235], v[16:19]
	v_mfma_f32_16x16x32_bf16 v[12:15], v[164:167], v[232:235], v[12:15]
	v_mfma_f32_16x16x32_bf16 v[56:59], v[168:171], v[204:207], v[56:59]
	v_mfma_f32_16x16x32_bf16 v[52:55], v[196:199], v[204:207], v[52:55]
	v_mfma_f32_16x16x32_bf16 v[40:43], v[168:171], v[212:215], v[40:43]
	v_mfma_f32_16x16x32_bf16 v[36:39], v[196:199], v[212:215], v[36:39]
	v_mfma_f32_16x16x32_bf16 v[24:27], v[168:171], v[220:223], v[24:27]
	v_mfma_f32_16x16x32_bf16 v[20:23], v[196:199], v[220:223], v[20:23]
	v_mfma_f32_16x16x32_bf16 v[8:11], v[168:171], v[228:231], v[8:11]
	v_mfma_f32_16x16x32_bf16 v[4:7], v[196:199], v[228:231], v[4:7]
	v_mfma_f32_16x16x32_bf16 v[56:59], v[172:175], v[208:211], v[56:59]
	v_mfma_f32_16x16x32_bf16 v[52:55], v[200:203], v[208:211], v[52:55]
	v_mfma_f32_16x16x32_bf16 v[40:43], v[172:175], v[216:219], v[40:43]
	v_mfma_f32_16x16x32_bf16 v[36:39], v[200:203], v[216:219], v[36:39]
	v_mfma_f32_16x16x32_bf16 v[24:27], v[172:175], v[224:227], v[24:27]
	v_mfma_f32_16x16x32_bf16 v[20:23], v[200:203], v[224:227], v[20:23]
	v_mfma_f32_16x16x32_bf16 v[8:11], v[172:175], v[232:235], v[8:11]
	v_mfma_f32_16x16x32_bf16 v[4:7], v[200:203], v[232:235], v[4:7]
	s_barrier
	s_add_i32 s27, s27, 2
	s_add_u32 s23, s23, 0x100
	s_addc_u32 s24, s24, 0
	s_add_u32 s12, s12, 0x100
	s_addc_u32 s13, s13, 0
	s_cmp_gt_u32 s27, 13
	s_cbranch_scc0 .LBB0_437
	s_and_b64 vcc, exec, s[48:49]
	s_cbranch_vccz .LBB0_440
	s_barrier

.Lsp_done_2:
.LBB0_620:
	s_add_u32 s16, s14, 0xfffc0080
	s_addc_u32 s17, s15, -1
	s_add_i32 s31, 0, 0x10000
	s_cmp_eq_u32 s27, 12
	s_cselect_b32 s19, s11, s17
	s_cselect_b32 s18, s22, s16
	v_add_u32_e32 v152, s31, v146
	s_cselect_b32 s17, s9, s24
	s_cselect_b32 s16, s28, s23
	s_add_i32 s41, 0, 0x14000
	ds_read_b128 v[142:145], v152
	ds_read_b128 v[160:163], v152 offset:1024
	ds_read_b128 v[164:167], v152 offset:2048
	ds_read_b128 v[168:171], v152 offset:3072
	v_add_u32_e32 v152, s41, v146
	ds_read_b128 v[172:175], v152
	ds_read_b128 v[190:193], v152 offset:1024
	ds_read_b128 v[194:197], v152 offset:2048
	ds_read_b128 v[198:201], v152 offset:3072
	v_lshl_add_u64 v[152:153], s[14:15], 0, v[140:141]
	s_add_i32 m0, s13, 0xc000
	ds_read_b128 v[202:205], v158
	ds_read_b128 v[206:209], v158 offset:1024
	ds_read_b128 v[210:213], v158 offset:2048
	ds_read_b128 v[214:217], v158 offset:3072
	ds_read_b128 v[218:221], v158 offset:4096
	ds_read_b128 v[222:225], v158 offset:5120
	ds_read_b128 v[226:229], v158 offset:6144
	ds_read_b128 v[230:233], v158 offset:7168
	global_load_lds_dwordx4 v[152:153], off
	v_lshl_add_u64 v[152:153], s[14:15], 0, v[138:139]
	s_add_i32 m0, s13, 0xe000
	s_nop 0
	global_load_lds_dwordx4 v[152:153], off
	s_waitcnt vmcnt(8)
	s_waitcnt lgkmcnt(0)
	s_barrier
	s_waitcnt lgkmcnt(0)
	v_mfma_f32_16x16x32_bf16 v[128:131], v[142:145], v[202:205], v[128:131]
	v_mfma_f32_16x16x32_bf16 v[120:123], v[164:167], v[202:205], v[120:123]
	v_mfma_f32_16x16x32_bf16 v[112:115], v[142:145], v[210:213], v[112:115]
	v_mfma_f32_16x16x32_bf16 v[104:107], v[164:167], v[210:213], v[104:107]
	v_mfma_f32_16x16x32_bf16 v[96:99], v[142:145], v[218:221], v[96:99]
	v_mfma_f32_16x16x32_bf16 v[88:91], v[164:167], v[218:221], v[88:91]
	v_mfma_f32_16x16x32_bf16 v[80:83], v[142:145], v[226:229], v[80:83]
	v_mfma_f32_16x16x32_bf16 v[72:75], v[164:167], v[226:229], v[72:75]
	v_mfma_f32_16x16x32_bf16 v[128:131], v[160:163], v[206:209], v[128:131]
	v_mfma_f32_16x16x32_bf16 v[120:123], v[168:171], v[206:209], v[120:123]
	v_mfma_f32_16x16x32_bf16 v[112:115], v[160:163], v[214:217], v[112:115]
	v_mfma_f32_16x16x32_bf16 v[104:107], v[168:171], v[214:217], v[104:107]
	v_mfma_f32_16x16x32_bf16 v[96:99], v[160:163], v[222:225], v[96:99]
	v_mfma_f32_16x16x32_bf16 v[88:91], v[168:171], v[222:225], v[88:91]
	v_mfma_f32_16x16x32_bf16 v[80:83], v[160:163], v[230:233], v[80:83]
	v_mfma_f32_16x16x32_bf16 v[72:75], v[168:171], v[230:233], v[72:75]
	v_mfma_f32_16x16x32_bf16 v[124:127], v[172:175], v[202:205], v[124:127]
	v_mfma_f32_16x16x32_bf16 v[116:119], v[194:197], v[202:205], v[116:119]
	v_mfma_f32_16x16x32_bf16 v[108:111], v[172:175], v[210:213], v[108:111]
	v_mfma_f32_16x16x32_bf16 v[100:103], v[194:197], v[210:213], v[100:103]
	v_mfma_f32_16x16x32_bf16 v[92:95], v[172:175], v[218:221], v[92:95]
	v_mfma_f32_16x16x32_bf16 v[84:87], v[194:197], v[218:221], v[84:87]
	v_mfma_f32_16x16x32_bf16 v[76:79], v[172:175], v[226:229], v[76:79]
	v_mfma_f32_16x16x32_bf16 v[68:71], v[194:197], v[226:229], v[68:71]
	v_mfma_f32_16x16x32_bf16 v[124:127], v[190:193], v[206:209], v[124:127]
	v_mfma_f32_16x16x32_bf16 v[116:119], v[198:201], v[206:209], v[116:119]
	v_mfma_f32_16x16x32_bf16 v[108:111], v[190:193], v[214:217], v[108:111]
	v_mfma_f32_16x16x32_bf16 v[100:103], v[198:201], v[214:217], v[100:103]
	v_mfma_f32_16x16x32_bf16 v[92:95], v[190:193], v[222:225], v[92:95]
	v_mfma_f32_16x16x32_bf16 v[84:87], v[198:201], v[222:225], v[84:87]
	v_mfma_f32_16x16x32_bf16 v[76:79], v[190:193], v[230:233], v[76:79]
	v_mfma_f32_16x16x32_bf16 v[68:71], v[198:201], v[230:233], v[68:71]
	s_barrier
	s_add_i32 s31, s31, s52
	v_lshl_add_u64 v[152:153], s[16:17], 0, v[132:133]
	s_mov_b32 m0, s31
	ds_read_b128 v[202:205], v158 offset:16384
	ds_read_b128 v[206:209], v158 offset:17408
	ds_read_b128 v[210:213], v158 offset:18432
	ds_read_b128 v[214:217], v158 offset:19456
	ds_read_b128 v[218:221], v158 offset:20480
	ds_read_b128 v[222:225], v158 offset:21504
	ds_read_b128 v[226:229], v158 offset:22528
	ds_read_b128 v[230:233], v158 offset:23552
	global_load_lds_dwordx4 v[152:153], off
	s_add_i32 m0, s31, 0x2000
	s_add_u32 s36, s16, 0x40000
	v_lshl_add_u64 v[234:235], s[16:17], 0, v[136:137]
	s_addc_u32 s37, s17, 0
	s_add_i32 s31, s41, s52
	global_load_lds_dwordx4 v[234:235], off
	v_lshl_add_u64 v[236:237], s[36:37], 0, v[132:133]
	s_mov_b32 m0, s31
	v_lshl_add_u64 v[238:239], s[18:19], 0, v[134:135]
	global_load_lds_dwordx4 v[236:237], off
	v_lshl_add_u64 v[236:237], s[36:37], 0, v[136:137]
	s_add_i32 m0, s31, 0x2000
	s_nop 0
	global_load_lds_dwordx4 v[236:237], off
	v_lshl_add_u64 v[236:237], s[18:19], 0, v[0:1]
	s_mov_b32 m0, s13
	s_nop 0
	global_load_lds_dwordx4 v[236:237], off
	s_mov_b32 m0, s53
	s_nop 0
	global_load_lds_dwordx4 v[238:239], off
	s_waitcnt vmcnt(8)
	s_waitcnt lgkmcnt(0)
	s_barrier
	s_waitcnt lgkmcnt(0)
	v_mfma_f32_16x16x32_bf16 v[64:67], v[142:145], v[202:205], v[64:67]
	v_mfma_f32_16x16x32_bf16 v[56:59], v[164:167], v[202:205], v[56:59]
	v_mfma_f32_16x16x32_bf16 v[48:51], v[142:145], v[210:213], v[48:51]
	v_mfma_f32_16x16x32_bf16 v[40:43], v[164:167], v[210:213], v[40:43]
	v_mfma_f32_16x16x32_bf16 v[32:35], v[142:145], v[218:221], v[32:35]
	v_mfma_f32_16x16x32_bf16 v[24:27], v[164:167], v[218:221], v[24:27]
	v_mfma_f32_16x16x32_bf16 v[16:19], v[142:145], v[226:229], v[16:19]
	v_mfma_f32_16x16x32_bf16 v[8:11], v[164:167], v[226:229], v[8:11]
	v_mfma_f32_16x16x32_bf16 v[64:67], v[160:163], v[206:209], v[64:67]
	v_mfma_f32_16x16x32_bf16 v[56:59], v[168:171], v[206:209], v[56:59]
	v_mfma_f32_16x16x32_bf16 v[48:51], v[160:163], v[214:217], v[48:51]
	v_mfma_f32_16x16x32_bf16 v[40:43], v[168:171], v[214:217], v[40:43]
	v_mfma_f32_16x16x32_bf16 v[32:35], v[160:163], v[222:225], v[32:35]
	v_mfma_f32_16x16x32_bf16 v[24:27], v[168:171], v[222:225], v[24:27]
	v_mfma_f32_16x16x32_bf16 v[16:19], v[160:163], v[230:233], v[16:19]
	v_mfma_f32_16x16x32_bf16 v[8:11], v[168:171], v[230:233], v[8:11]
	v_mfma_f32_16x16x32_bf16 v[60:63], v[172:175], v[202:205], v[60:63]
	v_mfma_f32_16x16x32_bf16 v[52:55], v[194:197], v[202:205], v[52:55]
	v_mfma_f32_16x16x32_bf16 v[44:47], v[172:175], v[210:213], v[44:47]
	v_mfma_f32_16x16x32_bf16 v[36:39], v[194:197], v[210:213], v[36:39]
	v_mfma_f32_16x16x32_bf16 v[28:31], v[172:175], v[218:221], v[28:31]
	v_mfma_f32_16x16x32_bf16 v[20:23], v[194:197], v[218:221], v[20:23]
	v_mfma_f32_16x16x32_bf16 v[12:15], v[172:175], v[226:229], v[12:15]
	v_mfma_f32_16x16x32_bf16 v[4:7], v[194:197], v[226:229], v[4:7]
	v_mfma_f32_16x16x32_bf16 v[60:63], v[190:193], v[206:209], v[60:63]
	v_mfma_f32_16x16x32_bf16 v[52:55], v[198:201], v[206:209], v[52:55]
	v_mfma_f32_16x16x32_bf16 v[44:47], v[190:193], v[214:217], v[44:47]
	v_mfma_f32_16x16x32_bf16 v[36:39], v[198:201], v[214:217], v[36:39]
	v_mfma_f32_16x16x32_bf16 v[28:31], v[190:193], v[222:225], v[28:31]
	v_mfma_f32_16x16x32_bf16 v[20:23], v[198:201], v[222:225], v[20:23]
	v_mfma_f32_16x16x32_bf16 v[12:15], v[190:193], v[230:233], v[12:15]
	v_mfma_f32_16x16x32_bf16 v[4:7], v[198:201], v[230:233], v[4:7]
	s_barrier
	s_add_i32 s31, 0, 0x18000
	v_add_u32_e32 v159, s31, v146
	s_add_i32 s36, 0, 0x1c000
	ds_read_b128 v[142:145], v159
	ds_read_b128 v[160:163], v159 offset:1024
	ds_read_b128 v[164:167], v159 offset:2048
	ds_read_b128 v[168:171], v159 offset:3072
	v_add_u32_e32 v159, s36, v146
	ds_read_b128 v[172:175], v159
	ds_read_b128 v[190:193], v159 offset:1024
	ds_read_b128 v[194:197], v159 offset:2048
	ds_read_b128 v[198:201], v159 offset:3072
	s_add_u32 s18, s18, 0x40000
	s_addc_u32 s19, s19, 0
	s_mov_b32 m0, s54
	v_lshl_add_u64 v[240:241], s[18:19], 0, v[0:1]
	ds_read_b128 v[202:205], v158 offset:32768
	ds_read_b128 v[206:209], v158 offset:33792
	ds_read_b128 v[210:213], v158 offset:34816
	ds_read_b128 v[214:217], v158 offset:35840
	ds_read_b128 v[218:221], v158 offset:36864
	ds_read_b128 v[222:225], v158 offset:37888
	ds_read_b128 v[226:229], v158 offset:38912
	ds_read_b128 v[230:233], v158 offset:39936
	global_load_lds_dwordx4 v[240:241], off
	v_lshl_add_u64 v[240:241], s[18:19], 0, v[134:135]
	s_mov_b32 m0, s55
	s_nop 0
	global_load_lds_dwordx4 v[240:241], off
	s_waitcnt vmcnt(8)
	s_waitcnt lgkmcnt(0)
	s_barrier
	s_waitcnt lgkmcnt(0)
	v_mfma_f32_16x16x32_bf16 v[128:131], v[142:145], v[202:205], v[128:131]
	v_mfma_f32_16x16x32_bf16 v[120:123], v[164:167], v[202:205], v[120:123]
	v_mfma_f32_16x16x32_bf16 v[112:115], v[142:145], v[210:213], v[112:115]
	v_mfma_f32_16x16x32_bf16 v[104:107], v[164:167], v[210:213], v[104:107]
	v_mfma_f32_16x16x32_bf16 v[96:99], v[142:145], v[218:221], v[96:99]
	v_mfma_f32_16x16x32_bf16 v[88:91], v[164:167], v[218:221], v[88:91]
	v_mfma_f32_16x16x32_bf16 v[80:83], v[142:145], v[226:229], v[80:83]
	v_mfma_f32_16x16x32_bf16 v[72:75], v[164:167], v[226:229], v[72:75]
	v_mfma_f32_16x16x32_bf16 v[128:131], v[160:163], v[206:209], v[128:131]
	v_mfma_f32_16x16x32_bf16 v[120:123], v[168:171], v[206:209], v[120:123]
	v_mfma_f32_16x16x32_bf16 v[112:115], v[160:163], v[214:217], v[112:115]
	v_mfma_f32_16x16x32_bf16 v[104:107], v[168:171], v[214:217], v[104:107]
	v_mfma_f32_16x16x32_bf16 v[96:99], v[160:163], v[222:225], v[96:99]
	v_mfma_f32_16x16x32_bf16 v[88:91], v[168:171], v[222:225], v[88:91]
	v_mfma_f32_16x16x32_bf16 v[80:83], v[160:163], v[230:233], v[80:83]
	v_mfma_f32_16x16x32_bf16 v[72:75], v[168:171], v[230:233], v[72:75]
	v_mfma_f32_16x16x32_bf16 v[124:127], v[172:175], v[202:205], v[124:127]
	v_mfma_f32_16x16x32_bf16 v[116:119], v[194:197], v[202:205], v[116:119]
	v_mfma_f32_16x16x32_bf16 v[108:111], v[172:175], v[210:213], v[108:111]
	v_mfma_f32_16x16x32_bf16 v[100:103], v[194:197], v[210:213], v[100:103]
	v_mfma_f32_16x16x32_bf16 v[92:95], v[172:175], v[218:221], v[92:95]
	v_mfma_f32_16x16x32_bf16 v[84:87], v[194:197], v[218:221], v[84:87]
	v_mfma_f32_16x16x32_bf16 v[76:79], v[172:175], v[226:229], v[76:79]
	v_mfma_f32_16x16x32_bf16 v[68:71], v[194:197], v[226:229], v[68:71]
	v_mfma_f32_16x16x32_bf16 v[124:127], v[190:193], v[206:209], v[124:127]
	v_mfma_f32_16x16x32_bf16 v[116:119], v[198:201], v[206:209], v[116:119]
	v_mfma_f32_16x16x32_bf16 v[108:111], v[190:193], v[214:217], v[108:111]
	v_mfma_f32_16x16x32_bf16 v[100:103], v[198:201], v[214:217], v[100:103]
	v_mfma_f32_16x16x32_bf16 v[92:95], v[190:193], v[222:225], v[92:95]
	v_mfma_f32_16x16x32_bf16 v[84:87], v[198:201], v[222:225], v[84:87]
	v_mfma_f32_16x16x32_bf16 v[76:79], v[190:193], v[230:233], v[76:79]
	v_mfma_f32_16x16x32_bf16 v[68:71], v[198:201], v[230:233], v[68:71]
	s_barrier
	s_add_i32 s18, s31, s52
	v_lshl_add_u64 v[152:153], v[152:153], 0, s[84:85]
	s_mov_b32 m0, s18
	ds_read_b128 v[202:205], v158 offset:49152
	ds_read_b128 v[206:209], v158 offset:50176
	ds_read_b128 v[210:213], v158 offset:51200
	ds_read_b128 v[214:217], v158 offset:52224
	ds_read_b128 v[218:221], v158 offset:53248
	ds_read_b128 v[222:225], v158 offset:54272
	ds_read_b128 v[226:229], v158 offset:55296
	ds_read_b128 v[230:233], v158 offset:56320
	global_load_lds_dwordx4 v[152:153], off
	s_add_i32 m0, s18, 0x2000
	s_add_u32 s16, s16, 0x40080
	v_lshl_add_u64 v[152:153], v[234:235], 0, s[84:85]
	s_addc_u32 s17, s17, 0
	s_add_i32 s18, s36, s52
	global_load_lds_dwordx4 v[152:153], off
	v_lshl_add_u64 v[152:153], s[16:17], 0, v[132:133]
	s_mov_b32 m0, s18
	s_nop 0
	global_load_lds_dwordx4 v[152:153], off
	v_lshl_add_u64 v[152:153], s[16:17], 0, v[136:137]
	s_add_i32 m0, s18, 0x2000
	s_nop 0
	global_load_lds_dwordx4 v[152:153], off
	v_lshl_add_u64 v[152:153], v[236:237], 0, s[84:85]
	s_mov_b32 m0, s58
	s_nop 0
	global_load_lds_dwordx4 v[152:153], off
	v_lshl_add_u64 v[152:153], v[238:239], 0, s[84:85]
	s_mov_b32 m0, s59
	s_nop 0
	global_load_lds_dwordx4 v[152:153], off
	s_waitcnt vmcnt(8)
	s_waitcnt lgkmcnt(0)
	s_barrier
	s_waitcnt lgkmcnt(0)
	v_mfma_f32_16x16x32_bf16 v[64:67], v[142:145], v[202:205], v[64:67]
	v_mfma_f32_16x16x32_bf16 v[56:59], v[164:167], v[202:205], v[56:59]
	v_mfma_f32_16x16x32_bf16 v[48:51], v[142:145], v[210:213], v[48:51]
	v_mfma_f32_16x16x32_bf16 v[40:43], v[164:167], v[210:213], v[40:43]
	v_mfma_f32_16x16x32_bf16 v[32:35], v[142:145], v[218:221], v[32:35]
	v_mfma_f32_16x16x32_bf16 v[24:27], v[164:167], v[218:221], v[24:27]
	v_mfma_f32_16x16x32_bf16 v[16:19], v[142:145], v[226:229], v[16:19]
	v_mfma_f32_16x16x32_bf16 v[8:11], v[164:167], v[226:229], v[8:11]
	v_mfma_f32_16x16x32_bf16 v[64:67], v[160:163], v[206:209], v[64:67]
	v_mfma_f32_16x16x32_bf16 v[56:59], v[168:171], v[206:209], v[56:59]
	v_mfma_f32_16x16x32_bf16 v[48:51], v[160:163], v[214:217], v[48:51]
	v_mfma_f32_16x16x32_bf16 v[40:43], v[168:171], v[214:217], v[40:43]
	v_mfma_f32_16x16x32_bf16 v[32:35], v[160:163], v[222:225], v[32:35]
	v_mfma_f32_16x16x32_bf16 v[24:27], v[168:171], v[222:225], v[24:27]
	v_mfma_f32_16x16x32_bf16 v[16:19], v[160:163], v[230:233], v[16:19]
	v_mfma_f32_16x16x32_bf16 v[8:11], v[168:171], v[230:233], v[8:11]
	v_mfma_f32_16x16x32_bf16 v[60:63], v[172:175], v[202:205], v[60:63]
	v_mfma_f32_16x16x32_bf16 v[52:55], v[194:197], v[202:205], v[52:55]
	v_mfma_f32_16x16x32_bf16 v[44:47], v[172:175], v[210:213], v[44:47]
	v_mfma_f32_16x16x32_bf16 v[36:39], v[194:197], v[210:213], v[36:39]
	v_mfma_f32_16x16x32_bf16 v[28:31], v[172:175], v[218:221], v[28:31]
	v_mfma_f32_16x16x32_bf16 v[20:23], v[194:197], v[218:221], v[20:23]
	v_mfma_f32_16x16x32_bf16 v[12:15], v[172:175], v[226:229], v[12:15]
	v_mfma_f32_16x16x32_bf16 v[4:7], v[194:197], v[226:229], v[4:7]
	v_mfma_f32_16x16x32_bf16 v[60:63], v[190:193], v[206:209], v[60:63]
	v_mfma_f32_16x16x32_bf16 v[52:55], v[198:201], v[206:209], v[52:55]
	v_mfma_f32_16x16x32_bf16 v[44:47], v[190:193], v[214:217], v[44:47]
	v_mfma_f32_16x16x32_bf16 v[36:39], v[198:201], v[214:217], v[36:39]
	v_mfma_f32_16x16x32_bf16 v[28:31], v[190:193], v[222:225], v[28:31]
	v_mfma_f32_16x16x32_bf16 v[20:23], v[198:201], v[222:225], v[20:23]
	v_mfma_f32_16x16x32_bf16 v[12:15], v[190:193], v[230:233], v[12:15]
	v_mfma_f32_16x16x32_bf16 v[4:7], v[198:201], v[230:233], v[4:7]
	s_barrier
	s_add_i32 s27, s27, 2
	s_add_u32 s23, s23, 0x100
	s_addc_u32 s24, s24, 0
	s_add_u32 s14, s14, 0x100
	s_addc_u32 s15, s15, 0
	s_cmp_gt_u32 s27, 13
	s_cbranch_scc0 .LBB0_620
	s_and_b64 vcc, exec, s[6:7]
	s_cbranch_vccz .LBB0_623
	s_barrier

.Lsp_done_3:
.LBB0_676:
	s_add_i32 s24, s12, 2
	s_add_u32 s27, s10, 0x80
	s_addc_u32 s13, s11, 0
	s_add_i32 s31, 0, 0x10000
	s_cmp_eq_u32 s14, s12
	s_cselect_b32 s13, s1, s13
	s_cselect_b32 s12, s0, s27
	s_cselect_b32 s37, s49, s23
	s_cselect_b32 s36, s48, s15
	s_add_i32 s27, 0, 0x14000
	v_add_u32_e32 v144, s31, v170
	v_add_u32_e32 v152, s27, v170
	ds_read_b128 v[128:131], v144
	ds_read_b128 v[132:135], v144 offset:1024
	ds_read_b128 v[136:139], v144 offset:2048
	ds_read_b128 v[144:147], v144 offset:3072
	ds_read_b128 v[164:167], v152
	ds_read_b128 v[190:193], v152 offset:1024
	ds_read_b128 v[194:197], v152 offset:2048
	ds_read_b128 v[198:201], v152 offset:3072
	v_lshl_add_u64 v[152:153], s[10:11], 0, v[162:163]
	s_add_i32 m0, s51, 0xc000
	ds_read_b128 v[202:205], v172
	ds_read_b128 v[206:209], v172 offset:1024
	ds_read_b128 v[210:213], v172 offset:2048
	ds_read_b128 v[214:217], v172 offset:3072
	ds_read_b128 v[218:221], v172 offset:4096
	ds_read_b128 v[222:225], v172 offset:5120
	ds_read_b128 v[226:229], v172 offset:6144
	ds_read_b128 v[230:233], v172 offset:7168
	global_load_lds_dwordx4 v[152:153], off
	v_lshl_add_u64 v[152:153], s[10:11], 0, v[160:161]
	s_add_i32 m0, s51, 0xe000
	s_nop 0
	global_load_lds_dwordx4 v[152:153], off
	s_waitcnt vmcnt(8)
	s_waitcnt lgkmcnt(0)
	s_barrier
	s_waitcnt lgkmcnt(0)
	v_mfma_f32_16x16x32_bf16 v[140:143], v[128:131], v[202:205], v[140:143]
	v_mfma_f32_16x16x32_bf16 v[124:127], v[136:139], v[202:205], v[124:127]
	v_mfma_f32_16x16x32_bf16 v[112:115], v[128:131], v[210:213], v[112:115]
	v_mfma_f32_16x16x32_bf16 v[108:111], v[136:139], v[210:213], v[108:111]
	v_mfma_f32_16x16x32_bf16 v[96:99], v[128:131], v[218:221], v[96:99]
	v_mfma_f32_16x16x32_bf16 v[92:95], v[136:139], v[218:221], v[92:95]
	v_mfma_f32_16x16x32_bf16 v[80:83], v[128:131], v[226:229], v[80:83]
	v_mfma_f32_16x16x32_bf16 v[76:79], v[136:139], v[226:229], v[76:79]
	v_mfma_f32_16x16x32_bf16 v[140:143], v[132:135], v[206:209], v[140:143]
	v_mfma_f32_16x16x32_bf16 v[124:127], v[144:147], v[206:209], v[124:127]
	v_mfma_f32_16x16x32_bf16 v[112:115], v[132:135], v[214:217], v[112:115]
	v_mfma_f32_16x16x32_bf16 v[108:111], v[144:147], v[214:217], v[108:111]
	v_mfma_f32_16x16x32_bf16 v[96:99], v[132:135], v[222:225], v[96:99]
	v_mfma_f32_16x16x32_bf16 v[92:95], v[144:147], v[222:225], v[92:95]
	v_mfma_f32_16x16x32_bf16 v[80:83], v[132:135], v[230:233], v[80:83]
	v_mfma_f32_16x16x32_bf16 v[76:79], v[144:147], v[230:233], v[76:79]
	v_mfma_f32_16x16x32_bf16 v[120:123], v[164:167], v[202:205], v[120:123]
	v_mfma_f32_16x16x32_bf16 v[116:119], v[194:197], v[202:205], v[116:119]
	v_mfma_f32_16x16x32_bf16 v[104:107], v[164:167], v[210:213], v[104:107]
	v_mfma_f32_16x16x32_bf16 v[100:103], v[194:197], v[210:213], v[100:103]
	v_mfma_f32_16x16x32_bf16 v[88:91], v[164:167], v[218:221], v[88:91]
	v_mfma_f32_16x16x32_bf16 v[84:87], v[194:197], v[218:221], v[84:87]
	v_mfma_f32_16x16x32_bf16 v[72:75], v[164:167], v[226:229], v[72:75]
	v_mfma_f32_16x16x32_bf16 v[68:71], v[194:197], v[226:229], v[68:71]
	v_mfma_f32_16x16x32_bf16 v[120:123], v[190:193], v[206:209], v[120:123]
	v_mfma_f32_16x16x32_bf16 v[116:119], v[198:201], v[206:209], v[116:119]
	v_mfma_f32_16x16x32_bf16 v[104:107], v[190:193], v[214:217], v[104:107]
	v_mfma_f32_16x16x32_bf16 v[100:103], v[198:201], v[214:217], v[100:103]
	v_mfma_f32_16x16x32_bf16 v[88:91], v[190:193], v[222:225], v[88:91]
	v_mfma_f32_16x16x32_bf16 v[84:87], v[198:201], v[222:225], v[84:87]
	v_mfma_f32_16x16x32_bf16 v[72:75], v[190:193], v[230:233], v[72:75]
	v_mfma_f32_16x16x32_bf16 v[68:71], v[198:201], v[230:233], v[68:71]
	s_barrier
	s_add_i32 s31, s31, s19
	v_lshl_add_u64 v[152:153], s[36:37], 0, v[0:1]
	s_mov_b32 m0, s31
	ds_read_b128 v[202:205], v172 offset:16384
	ds_read_b128 v[206:209], v172 offset:17408
	ds_read_b128 v[210:213], v172 offset:18432
	ds_read_b128 v[214:217], v172 offset:19456
	ds_read_b128 v[218:221], v172 offset:20480
	ds_read_b128 v[222:225], v172 offset:21504
	ds_read_b128 v[226:229], v172 offset:22528
	ds_read_b128 v[230:233], v172 offset:23552
	global_load_lds_dwordx4 v[152:153], off
	s_add_i32 m0, s31, 0x2000
	v_lshl_add_u64 v[168:169], s[36:37], 0, v[158:159]
	s_add_u32 s36, s36, s88
	s_addc_u32 s37, s37, 0
	s_add_i32 s27, s27, s19
	global_load_lds_dwordx4 v[168:169], off
	v_lshl_add_u64 v[174:175], s[36:37], 0, v[0:1]
	s_mov_b32 m0, s27
	v_lshl_add_u64 v[234:235], s[36:37], 0, v[158:159]
	global_load_lds_dwordx4 v[174:175], off
	s_add_i32 m0, s27, 0x2000
	v_lshl_add_u64 v[236:237], s[12:13], 0, v[0:1]
	global_load_lds_dwordx4 v[234:235], off
	s_mov_b32 m0, s51
	v_lshl_add_u64 v[238:239], s[12:13], 0, v[158:159]
	global_load_lds_dwordx4 v[236:237], off
	s_mov_b32 m0, s52
	s_nop 0
	global_load_lds_dwordx4 v[238:239], off
	s_waitcnt vmcnt(8)
	s_waitcnt lgkmcnt(0)
	s_barrier
	s_waitcnt lgkmcnt(0)
	v_mfma_f32_16x16x32_bf16 v[64:67], v[128:131], v[202:205], v[64:67]
	v_mfma_f32_16x16x32_bf16 v[60:63], v[136:139], v[202:205], v[60:63]
	v_mfma_f32_16x16x32_bf16 v[48:51], v[128:131], v[210:213], v[48:51]
	v_mfma_f32_16x16x32_bf16 v[44:47], v[136:139], v[210:213], v[44:47]
	v_mfma_f32_16x16x32_bf16 v[32:35], v[128:131], v[218:221], v[32:35]
	v_mfma_f32_16x16x32_bf16 v[28:31], v[136:139], v[218:221], v[28:31]
	v_mfma_f32_16x16x32_bf16 v[16:19], v[128:131], v[226:229], v[16:19]
	v_mfma_f32_16x16x32_bf16 v[12:15], v[136:139], v[226:229], v[12:15]
	v_mfma_f32_16x16x32_bf16 v[64:67], v[132:135], v[206:209], v[64:67]
	v_mfma_f32_16x16x32_bf16 v[60:63], v[144:147], v[206:209], v[60:63]
	v_mfma_f32_16x16x32_bf16 v[48:51], v[132:135], v[214:217], v[48:51]
	v_mfma_f32_16x16x32_bf16 v[44:47], v[144:147], v[214:217], v[44:47]
	v_mfma_f32_16x16x32_bf16 v[32:35], v[132:135], v[222:225], v[32:35]
	v_mfma_f32_16x16x32_bf16 v[28:31], v[144:147], v[222:225], v[28:31]
	v_mfma_f32_16x16x32_bf16 v[16:19], v[132:135], v[230:233], v[16:19]
	v_mfma_f32_16x16x32_bf16 v[12:15], v[144:147], v[230:233], v[12:15]
	v_mfma_f32_16x16x32_bf16 v[56:59], v[164:167], v[202:205], v[56:59]
	v_mfma_f32_16x16x32_bf16 v[52:55], v[194:197], v[202:205], v[52:55]
	v_mfma_f32_16x16x32_bf16 v[40:43], v[164:167], v[210:213], v[40:43]
	v_mfma_f32_16x16x32_bf16 v[36:39], v[194:197], v[210:213], v[36:39]
	v_mfma_f32_16x16x32_bf16 v[24:27], v[164:167], v[218:221], v[24:27]
	v_mfma_f32_16x16x32_bf16 v[20:23], v[194:197], v[218:221], v[20:23]
	v_mfma_f32_16x16x32_bf16 v[8:11], v[164:167], v[226:229], v[8:11]
	v_mfma_f32_16x16x32_bf16 v[4:7], v[194:197], v[226:229], v[4:7]
	v_mfma_f32_16x16x32_bf16 v[56:59], v[190:193], v[206:209], v[56:59]
	v_mfma_f32_16x16x32_bf16 v[52:55], v[198:201], v[206:209], v[52:55]
	v_mfma_f32_16x16x32_bf16 v[40:43], v[190:193], v[214:217], v[40:43]
	v_mfma_f32_16x16x32_bf16 v[36:39], v[198:201], v[214:217], v[36:39]
	v_mfma_f32_16x16x32_bf16 v[24:27], v[190:193], v[222:225], v[24:27]
	v_mfma_f32_16x16x32_bf16 v[20:23], v[198:201], v[222:225], v[20:23]
	v_mfma_f32_16x16x32_bf16 v[8:11], v[190:193], v[230:233], v[8:11]
	v_mfma_f32_16x16x32_bf16 v[4:7], v[198:201], v[230:233], v[4:7]
	s_barrier
	s_add_i32 s27, 0, 0x18000
	s_add_i32 s31, 0, 0x1c000
	v_add_u32_e32 v144, s27, v170
	v_add_u32_e32 v173, s31, v170
	ds_read_b128 v[128:131], v144
	ds_read_b128 v[132:135], v144 offset:1024
	ds_read_b128 v[136:139], v144 offset:2048
	ds_read_b128 v[144:147], v144 offset:3072
	ds_read_b128 v[164:167], v173
	ds_read_b128 v[190:193], v173 offset:1024
	ds_read_b128 v[194:197], v173 offset:2048
	ds_read_b128 v[198:201], v173 offset:3072
	s_add_u32 s12, s12, s88
	s_addc_u32 s13, s13, 0
	s_mov_b32 m0, s53
	v_lshl_add_u64 v[240:241], s[12:13], 0, v[0:1]
	ds_read_b128 v[202:205], v172 offset:32768
	ds_read_b128 v[206:209], v172 offset:33792
	ds_read_b128 v[210:213], v172 offset:34816
	ds_read_b128 v[214:217], v172 offset:35840
	ds_read_b128 v[218:221], v172 offset:36864
	ds_read_b128 v[222:225], v172 offset:37888
	ds_read_b128 v[226:229], v172 offset:38912
	ds_read_b128 v[230:233], v172 offset:39936
	global_load_lds_dwordx4 v[240:241], off
	v_lshl_add_u64 v[240:241], s[12:13], 0, v[158:159]
	s_mov_b32 m0, s54
	s_nop 0
	global_load_lds_dwordx4 v[240:241], off
	s_waitcnt vmcnt(8)
	s_waitcnt lgkmcnt(0)
	s_barrier
	s_waitcnt lgkmcnt(0)
	v_mfma_f32_16x16x32_bf16 v[140:143], v[128:131], v[202:205], v[140:143]
	v_mfma_f32_16x16x32_bf16 v[124:127], v[136:139], v[202:205], v[124:127]
	v_mfma_f32_16x16x32_bf16 v[112:115], v[128:131], v[210:213], v[112:115]
	v_mfma_f32_16x16x32_bf16 v[108:111], v[136:139], v[210:213], v[108:111]
	v_mfma_f32_16x16x32_bf16 v[96:99], v[128:131], v[218:221], v[96:99]
	v_mfma_f32_16x16x32_bf16 v[92:95], v[136:139], v[218:221], v[92:95]
	v_mfma_f32_16x16x32_bf16 v[80:83], v[128:131], v[226:229], v[80:83]
	v_mfma_f32_16x16x32_bf16 v[76:79], v[136:139], v[226:229], v[76:79]
	v_mfma_f32_16x16x32_bf16 v[140:143], v[132:135], v[206:209], v[140:143]
	v_mfma_f32_16x16x32_bf16 v[124:127], v[144:147], v[206:209], v[124:127]
	v_mfma_f32_16x16x32_bf16 v[112:115], v[132:135], v[214:217], v[112:115]
	v_mfma_f32_16x16x32_bf16 v[108:111], v[144:147], v[214:217], v[108:111]
	v_mfma_f32_16x16x32_bf16 v[96:99], v[132:135], v[222:225], v[96:99]
	v_mfma_f32_16x16x32_bf16 v[92:95], v[144:147], v[222:225], v[92:95]
	v_mfma_f32_16x16x32_bf16 v[80:83], v[132:135], v[230:233], v[80:83]
	v_mfma_f32_16x16x32_bf16 v[76:79], v[144:147], v[230:233], v[76:79]
	v_mfma_f32_16x16x32_bf16 v[120:123], v[164:167], v[202:205], v[120:123]
	v_mfma_f32_16x16x32_bf16 v[116:119], v[194:197], v[202:205], v[116:119]
	v_mfma_f32_16x16x32_bf16 v[104:107], v[164:167], v[210:213], v[104:107]
	v_mfma_f32_16x16x32_bf16 v[100:103], v[194:197], v[210:213], v[100:103]
	v_mfma_f32_16x16x32_bf16 v[88:91], v[164:167], v[218:221], v[88:91]
	v_mfma_f32_16x16x32_bf16 v[84:87], v[194:197], v[218:221], v[84:87]
	v_mfma_f32_16x16x32_bf16 v[72:75], v[164:167], v[226:229], v[72:75]
	v_mfma_f32_16x16x32_bf16 v[68:71], v[194:197], v[226:229], v[68:71]
	v_mfma_f32_16x16x32_bf16 v[120:123], v[190:193], v[206:209], v[120:123]
	v_mfma_f32_16x16x32_bf16 v[116:119], v[198:201], v[206:209], v[116:119]
	v_mfma_f32_16x16x32_bf16 v[104:107], v[190:193], v[214:217], v[104:107]
	v_mfma_f32_16x16x32_bf16 v[100:103], v[198:201], v[214:217], v[100:103]
	v_mfma_f32_16x16x32_bf16 v[88:91], v[190:193], v[222:225], v[88:91]
	v_mfma_f32_16x16x32_bf16 v[84:87], v[198:201], v[222:225], v[84:87]
	v_mfma_f32_16x16x32_bf16 v[72:75], v[190:193], v[230:233], v[72:75]
	v_mfma_f32_16x16x32_bf16 v[68:71], v[198:201], v[230:233], v[68:71]
	s_barrier
	s_add_i32 s12, s27, s19
	v_lshl_add_u64 v[152:153], v[152:153], 0, s[84:85]
	s_mov_b32 m0, s12
	ds_read_b128 v[202:205], v172 offset:49152
	ds_read_b128 v[206:209], v172 offset:50176
	ds_read_b128 v[210:213], v172 offset:51200
	ds_read_b128 v[214:217], v172 offset:52224
	ds_read_b128 v[218:221], v172 offset:53248
	ds_read_b128 v[222:225], v172 offset:54272
	ds_read_b128 v[226:229], v172 offset:55296
	ds_read_b128 v[230:233], v172 offset:56320
	global_load_lds_dwordx4 v[152:153], off
	v_lshl_add_u64 v[152:153], v[168:169], 0, s[84:85]
	s_add_i32 m0, s12, 0x2000
	s_add_i32 s12, s31, s19
	global_load_lds_dwordx4 v[152:153], off
	v_lshl_add_u64 v[152:153], v[174:175], 0, s[84:85]
	s_mov_b32 m0, s12
	s_nop 0
	global_load_lds_dwordx4 v[152:153], off
	v_lshl_add_u64 v[152:153], v[234:235], 0, s[84:85]
	s_add_i32 m0, s12, 0x2000
	s_nop 0
	global_load_lds_dwordx4 v[152:153], off
	v_lshl_add_u64 v[152:153], v[236:237], 0, s[84:85]
	s_mov_b32 m0, s55
	s_nop 0
	global_load_lds_dwordx4 v[152:153], off
	v_lshl_add_u64 v[152:153], v[238:239], 0, s[84:85]
	s_mov_b32 m0, s58
	s_nop 0
	global_load_lds_dwordx4 v[152:153], off
	s_waitcnt vmcnt(8)
	s_waitcnt lgkmcnt(0)
	s_barrier
	s_waitcnt lgkmcnt(0)
	v_mfma_f32_16x16x32_bf16 v[64:67], v[128:131], v[202:205], v[64:67]
	v_mfma_f32_16x16x32_bf16 v[60:63], v[136:139], v[202:205], v[60:63]
	v_mfma_f32_16x16x32_bf16 v[48:51], v[128:131], v[210:213], v[48:51]
	v_mfma_f32_16x16x32_bf16 v[44:47], v[136:139], v[210:213], v[44:47]
	v_mfma_f32_16x16x32_bf16 v[32:35], v[128:131], v[218:221], v[32:35]
	v_mfma_f32_16x16x32_bf16 v[28:31], v[136:139], v[218:221], v[28:31]
	v_mfma_f32_16x16x32_bf16 v[16:19], v[128:131], v[226:229], v[16:19]
	v_mfma_f32_16x16x32_bf16 v[12:15], v[136:139], v[226:229], v[12:15]
	v_mfma_f32_16x16x32_bf16 v[64:67], v[132:135], v[206:209], v[64:67]
	v_mfma_f32_16x16x32_bf16 v[60:63], v[144:147], v[206:209], v[60:63]
	v_mfma_f32_16x16x32_bf16 v[48:51], v[132:135], v[214:217], v[48:51]
	v_mfma_f32_16x16x32_bf16 v[44:47], v[144:147], v[214:217], v[44:47]
	v_mfma_f32_16x16x32_bf16 v[32:35], v[132:135], v[222:225], v[32:35]
	v_mfma_f32_16x16x32_bf16 v[28:31], v[144:147], v[222:225], v[28:31]
	v_mfma_f32_16x16x32_bf16 v[16:19], v[132:135], v[230:233], v[16:19]
	v_mfma_f32_16x16x32_bf16 v[12:15], v[144:147], v[230:233], v[12:15]
	v_mfma_f32_16x16x32_bf16 v[56:59], v[164:167], v[202:205], v[56:59]
	v_mfma_f32_16x16x32_bf16 v[52:55], v[194:197], v[202:205], v[52:55]
	v_mfma_f32_16x16x32_bf16 v[40:43], v[164:167], v[210:213], v[40:43]
	v_mfma_f32_16x16x32_bf16 v[36:39], v[194:197], v[210:213], v[36:39]
	v_mfma_f32_16x16x32_bf16 v[24:27], v[164:167], v[218:221], v[24:27]
	v_mfma_f32_16x16x32_bf16 v[20:23], v[194:197], v[218:221], v[20:23]
	v_mfma_f32_16x16x32_bf16 v[8:11], v[164:167], v[226:229], v[8:11]
	v_mfma_f32_16x16x32_bf16 v[4:7], v[194:197], v[226:229], v[4:7]
	v_mfma_f32_16x16x32_bf16 v[56:59], v[190:193], v[206:209], v[56:59]
	v_mfma_f32_16x16x32_bf16 v[52:55], v[198:201], v[206:209], v[52:55]
	v_mfma_f32_16x16x32_bf16 v[40:43], v[190:193], v[214:217], v[40:43]
	v_mfma_f32_16x16x32_bf16 v[36:39], v[198:201], v[214:217], v[36:39]
	v_mfma_f32_16x16x32_bf16 v[24:27], v[190:193], v[222:225], v[24:27]
	v_mfma_f32_16x16x32_bf16 v[20:23], v[198:201], v[222:225], v[20:23]
	v_mfma_f32_16x16x32_bf16 v[8:11], v[190:193], v[230:233], v[8:11]
	v_mfma_f32_16x16x32_bf16 v[4:7], v[198:201], v[230:233], v[4:7]
	s_barrier
	s_add_u32 s15, s15, 0x100
	s_addc_u32 s23, s23, 0
	s_add_u32 s10, s10, 0x100
	s_addc_u32 s11, s11, 0
	s_cmp_ge_i32 s24, s17
	s_mov_b32 s12, s24
	s_cbranch_scc0 .LBB0_676
	s_and_b64 vcc, exec, s[46:47]
	s_cbranch_vccz .LBB0_679
	s_barrier

.Lsp_done_4:
.LBB0_766:
	s_add_u32 s10, vcc_lo, 0xfffc0080
	s_addc_u32 s11, vcc_hi, -1
	s_add_i32 s36, 0, 0x10000
	s_cmp_eq_u32 s77, 12
	s_cselect_b32 s13, s59, s11
	s_cselect_b32 s12, s74, s10
	v_add_u32_e32 v152, s36, v3
	s_cselect_b32 s11, s9, s27
	s_cselect_b32 s10, s23, s24
	s_add_i32 s0, 0, 0x14000
	ds_read_b128 v[168:171], v152
	ds_read_b128 v[172:175], v152 offset:1024
	ds_read_b128 v[190:193], v152 offset:2048
	ds_read_b128 v[194:197], v152 offset:3072
	v_add_u32_e32 v152, s0, v3
	ds_read_b128 v[198:201], v152
	ds_read_b128 v[202:205], v152 offset:1024
	ds_read_b128 v[206:209], v152 offset:2048
	ds_read_b128 v[210:213], v152 offset:3072
	v_lshl_add_u64 v[164:165], vcc, 0, v[162:163]
	s_add_i32 m0, s15, 0xc000
	ds_read_b128 v[214:217], v167
	ds_read_b128 v[218:221], v167 offset:1024
	ds_read_b128 v[222:225], v167 offset:2048
	ds_read_b128 v[226:229], v167 offset:3072
	ds_read_b128 v[230:233], v167 offset:4096
	ds_read_b128 v[234:237], v167 offset:5120
	ds_read_b128 v[238:241], v167 offset:6144
	ds_read_b128 v[242:245], v167 offset:7168
	global_load_lds_dwordx4 v[164:165], off
	v_lshl_add_u64 v[164:165], vcc, 0, v[160:161]
	s_add_i32 m0, s15, 0xe000
	s_nop 0
	global_load_lds_dwordx4 v[164:165], off
	s_waitcnt vmcnt(8)
	s_waitcnt lgkmcnt(0)
	s_barrier
	s_waitcnt lgkmcnt(0)
	v_mfma_f32_16x16x32_bf16 v[128:131], v[168:171], v[214:217], v[128:131]
	v_mfma_f32_16x16x32_bf16 v[124:127], v[190:193], v[214:217], v[124:127]
	v_mfma_f32_16x16x32_bf16 v[116:119], v[168:171], v[222:225], v[116:119]
	v_mfma_f32_16x16x32_bf16 v[108:111], v[190:193], v[222:225], v[108:111]
	v_mfma_f32_16x16x32_bf16 v[100:103], v[168:171], v[230:233], v[100:103]
	v_mfma_f32_16x16x32_bf16 v[92:95], v[190:193], v[230:233], v[92:95]
	v_mfma_f32_16x16x32_bf16 v[84:87], v[168:171], v[238:241], v[84:87]
	v_mfma_f32_16x16x32_bf16 v[76:79], v[190:193], v[238:241], v[76:79]
	v_mfma_f32_16x16x32_bf16 v[128:131], v[172:175], v[218:221], v[128:131]
	v_mfma_f32_16x16x32_bf16 v[124:127], v[194:197], v[218:221], v[124:127]
	v_mfma_f32_16x16x32_bf16 v[116:119], v[172:175], v[226:229], v[116:119]
	v_mfma_f32_16x16x32_bf16 v[108:111], v[194:197], v[226:229], v[108:111]
	v_mfma_f32_16x16x32_bf16 v[100:103], v[172:175], v[234:237], v[100:103]
	v_mfma_f32_16x16x32_bf16 v[92:95], v[194:197], v[234:237], v[92:95]
	v_mfma_f32_16x16x32_bf16 v[84:87], v[172:175], v[242:245], v[84:87]
	v_mfma_f32_16x16x32_bf16 v[76:79], v[194:197], v[242:245], v[76:79]
	v_mfma_f32_16x16x32_bf16 v[120:123], v[198:201], v[214:217], v[120:123]
	v_mfma_f32_16x16x32_bf16 v[112:115], v[206:209], v[214:217], v[112:115]
	v_mfma_f32_16x16x32_bf16 v[104:107], v[198:201], v[222:225], v[104:107]
	v_mfma_f32_16x16x32_bf16 v[96:99], v[206:209], v[222:225], v[96:99]
	v_mfma_f32_16x16x32_bf16 v[88:91], v[198:201], v[230:233], v[88:91]
	v_mfma_f32_16x16x32_bf16 v[80:83], v[206:209], v[230:233], v[80:83]
	v_mfma_f32_16x16x32_bf16 v[72:75], v[198:201], v[238:241], v[72:75]
	v_mfma_f32_16x16x32_bf16 v[68:71], v[206:209], v[238:241], v[68:71]
	v_mfma_f32_16x16x32_bf16 v[120:123], v[202:205], v[218:221], v[120:123]
	v_mfma_f32_16x16x32_bf16 v[112:115], v[210:213], v[218:221], v[112:115]
	v_mfma_f32_16x16x32_bf16 v[104:107], v[202:205], v[226:229], v[104:107]
	v_mfma_f32_16x16x32_bf16 v[96:99], v[210:213], v[226:229], v[96:99]
	v_mfma_f32_16x16x32_bf16 v[88:91], v[202:205], v[234:237], v[88:91]
	v_mfma_f32_16x16x32_bf16 v[80:83], v[210:213], v[234:237], v[80:83]
	v_mfma_f32_16x16x32_bf16 v[72:75], v[202:205], v[242:245], v[72:75]
	v_mfma_f32_16x16x32_bf16 v[68:71], v[210:213], v[242:245], v[68:71]
	s_barrier
	s_add_i32 s1, s36, s90
	v_lshl_add_u64 v[164:165], s[10:11], 0, v[0:1]
	s_mov_b32 m0, s1
	ds_read_b128 v[214:217], v167 offset:16384
	ds_read_b128 v[218:221], v167 offset:17408
	ds_read_b128 v[222:225], v167 offset:18432
	ds_read_b128 v[226:229], v167 offset:19456
	ds_read_b128 v[230:233], v167 offset:20480
	ds_read_b128 v[234:237], v167 offset:21504
	ds_read_b128 v[238:241], v167 offset:22528
	ds_read_b128 v[242:245], v167 offset:23552
	global_load_lds_dwordx4 v[164:165], off
	s_add_i32 m0, s1, 0x2000
	s_add_u32 s36, s10, 0x40000
	v_lshl_add_u64 v[246:247], s[10:11], 0, v[132:133]
	s_addc_u32 s37, s11, 0
	s_add_i32 s0, s0, s90
	global_load_lds_dwordx4 v[246:247], off
	v_lshl_add_u64 v[248:249], s[36:37], 0, v[0:1]
	s_mov_b32 m0, s0
	v_lshl_add_u64 v[250:251], s[12:13], 0, v[132:133]
	global_load_lds_dwordx4 v[248:249], off
	v_lshl_add_u64 v[248:249], s[36:37], 0, v[132:133]
	s_add_i32 m0, s0, 0x2000
	s_nop 0
	global_load_lds_dwordx4 v[248:249], off
	v_lshl_add_u64 v[248:249], s[12:13], 0, v[0:1]
	s_mov_b32 m0, s15
	s_nop 0
	global_load_lds_dwordx4 v[248:249], off
	s_mov_b32 m0, s91
	s_nop 0
	global_load_lds_dwordx4 v[250:251], off
	s_waitcnt vmcnt(8)
	s_waitcnt lgkmcnt(0)
	s_barrier
	s_waitcnt lgkmcnt(0)
	v_mfma_f32_16x16x32_bf16 v[64:67], v[168:171], v[214:217], v[64:67]
	v_mfma_f32_16x16x32_bf16 v[60:63], v[190:193], v[214:217], v[60:63]
	v_mfma_f32_16x16x32_bf16 v[52:55], v[168:171], v[222:225], v[52:55]
	v_mfma_f32_16x16x32_bf16 v[44:47], v[190:193], v[222:225], v[44:47]
	v_mfma_f32_16x16x32_bf16 v[36:39], v[168:171], v[230:233], v[36:39]
	v_mfma_f32_16x16x32_bf16 v[28:31], v[190:193], v[230:233], v[28:31]
	v_mfma_f32_16x16x32_bf16 v[20:23], v[168:171], v[238:241], v[20:23]
	v_mfma_f32_16x16x32_bf16 v[12:15], v[190:193], v[238:241], v[12:15]
	v_mfma_f32_16x16x32_bf16 v[64:67], v[172:175], v[218:221], v[64:67]
	v_mfma_f32_16x16x32_bf16 v[60:63], v[194:197], v[218:221], v[60:63]
	v_mfma_f32_16x16x32_bf16 v[52:55], v[172:175], v[226:229], v[52:55]
	v_mfma_f32_16x16x32_bf16 v[44:47], v[194:197], v[226:229], v[44:47]
	v_mfma_f32_16x16x32_bf16 v[36:39], v[172:175], v[234:237], v[36:39]
	v_mfma_f32_16x16x32_bf16 v[28:31], v[194:197], v[234:237], v[28:31]
	v_mfma_f32_16x16x32_bf16 v[20:23], v[172:175], v[242:245], v[20:23]
	v_mfma_f32_16x16x32_bf16 v[12:15], v[194:197], v[242:245], v[12:15]
	v_mfma_f32_16x16x32_bf16 v[56:59], v[198:201], v[214:217], v[56:59]
	v_mfma_f32_16x16x32_bf16 v[48:51], v[206:209], v[214:217], v[48:51]
	v_mfma_f32_16x16x32_bf16 v[40:43], v[198:201], v[222:225], v[40:43]
	v_mfma_f32_16x16x32_bf16 v[32:35], v[206:209], v[222:225], v[32:35]
	v_mfma_f32_16x16x32_bf16 v[24:27], v[198:201], v[230:233], v[24:27]
	v_mfma_f32_16x16x32_bf16 v[16:19], v[206:209], v[230:233], v[16:19]
	v_mfma_f32_16x16x32_bf16 v[8:11], v[198:201], v[238:241], v[8:11]
	v_mfma_f32_16x16x32_bf16 v[4:7], v[206:209], v[238:241], v[4:7]
	v_mfma_f32_16x16x32_bf16 v[56:59], v[202:205], v[218:221], v[56:59]
	v_mfma_f32_16x16x32_bf16 v[48:51], v[210:213], v[218:221], v[48:51]
	v_mfma_f32_16x16x32_bf16 v[40:43], v[202:205], v[226:229], v[40:43]
	v_mfma_f32_16x16x32_bf16 v[32:35], v[210:213], v[226:229], v[32:35]
	v_mfma_f32_16x16x32_bf16 v[24:27], v[202:205], v[234:237], v[24:27]
	v_mfma_f32_16x16x32_bf16 v[16:19], v[210:213], v[234:237], v[16:19]
	v_mfma_f32_16x16x32_bf16 v[8:11], v[202:205], v[242:245], v[8:11]
	v_mfma_f32_16x16x32_bf16 v[4:7], v[210:213], v[242:245], v[4:7]
	s_barrier
	s_add_i32 s0, 0, 0x18000
	v_add_u32_e32 v152, s0, v3
	s_add_i32 s1, 0, 0x1c000
	ds_read_b128 v[168:171], v152
	ds_read_b128 v[172:175], v152 offset:1024
	ds_read_b128 v[190:193], v152 offset:2048
	ds_read_b128 v[194:197], v152 offset:3072
	v_add_u32_e32 v152, s1, v3
	ds_read_b128 v[198:201], v152
	ds_read_b128 v[202:205], v152 offset:1024
	ds_read_b128 v[206:209], v152 offset:2048
	ds_read_b128 v[210:213], v152 offset:3072
	s_add_u32 s12, s12, 0x40000
	s_addc_u32 s13, s13, 0
	s_mov_b32 m0, s31
	v_lshl_add_u64 v[152:153], s[12:13], 0, v[0:1]
	ds_read_b128 v[214:217], v167 offset:32768
	ds_read_b128 v[218:221], v167 offset:33792
	ds_read_b128 v[222:225], v167 offset:34816
	ds_read_b128 v[226:229], v167 offset:35840
	ds_read_b128 v[230:233], v167 offset:36864
	ds_read_b128 v[234:237], v167 offset:37888
	ds_read_b128 v[238:241], v167 offset:38912
	ds_read_b128 v[242:245], v167 offset:39936
	global_load_lds_dwordx4 v[152:153], off
	v_lshl_add_u64 v[152:153], s[12:13], 0, v[132:133]
	s_mov_b32 m0, s22
	s_nop 0
	global_load_lds_dwordx4 v[152:153], off
	s_waitcnt vmcnt(8)
	s_waitcnt lgkmcnt(0)
	s_barrier
	s_waitcnt lgkmcnt(0)
	v_mfma_f32_16x16x32_bf16 v[128:131], v[168:171], v[214:217], v[128:131]
	v_mfma_f32_16x16x32_bf16 v[124:127], v[190:193], v[214:217], v[124:127]
	v_mfma_f32_16x16x32_bf16 v[116:119], v[168:171], v[222:225], v[116:119]
	v_mfma_f32_16x16x32_bf16 v[108:111], v[190:193], v[222:225], v[108:111]
	v_mfma_f32_16x16x32_bf16 v[100:103], v[168:171], v[230:233], v[100:103]
	v_mfma_f32_16x16x32_bf16 v[92:95], v[190:193], v[230:233], v[92:95]
	v_mfma_f32_16x16x32_bf16 v[84:87], v[168:171], v[238:241], v[84:87]
	v_mfma_f32_16x16x32_bf16 v[76:79], v[190:193], v[238:241], v[76:79]
	v_mfma_f32_16x16x32_bf16 v[128:131], v[172:175], v[218:221], v[128:131]
	v_mfma_f32_16x16x32_bf16 v[124:127], v[194:197], v[218:221], v[124:127]
	v_mfma_f32_16x16x32_bf16 v[116:119], v[172:175], v[226:229], v[116:119]
	v_mfma_f32_16x16x32_bf16 v[108:111], v[194:197], v[226:229], v[108:111]
	v_mfma_f32_16x16x32_bf16 v[100:103], v[172:175], v[234:237], v[100:103]
	v_mfma_f32_16x16x32_bf16 v[92:95], v[194:197], v[234:237], v[92:95]
	v_mfma_f32_16x16x32_bf16 v[84:87], v[172:175], v[242:245], v[84:87]
	v_mfma_f32_16x16x32_bf16 v[76:79], v[194:197], v[242:245], v[76:79]
	v_mfma_f32_16x16x32_bf16 v[120:123], v[198:201], v[214:217], v[120:123]
	v_mfma_f32_16x16x32_bf16 v[112:115], v[206:209], v[214:217], v[112:115]
	v_mfma_f32_16x16x32_bf16 v[104:107], v[198:201], v[222:225], v[104:107]
	v_mfma_f32_16x16x32_bf16 v[96:99], v[206:209], v[222:225], v[96:99]
	v_mfma_f32_16x16x32_bf16 v[88:91], v[198:201], v[230:233], v[88:91]
	v_mfma_f32_16x16x32_bf16 v[80:83], v[206:209], v[230:233], v[80:83]
	v_mfma_f32_16x16x32_bf16 v[72:75], v[198:201], v[238:241], v[72:75]
	v_mfma_f32_16x16x32_bf16 v[68:71], v[206:209], v[238:241], v[68:71]
	v_mfma_f32_16x16x32_bf16 v[120:123], v[202:205], v[218:221], v[120:123]
	v_mfma_f32_16x16x32_bf16 v[112:115], v[210:213], v[218:221], v[112:115]
	v_mfma_f32_16x16x32_bf16 v[104:107], v[202:205], v[226:229], v[104:107]
	v_mfma_f32_16x16x32_bf16 v[96:99], v[210:213], v[226:229], v[96:99]
	v_mfma_f32_16x16x32_bf16 v[88:91], v[202:205], v[234:237], v[88:91]
	v_mfma_f32_16x16x32_bf16 v[80:83], v[210:213], v[234:237], v[80:83]
	v_mfma_f32_16x16x32_bf16 v[72:75], v[202:205], v[242:245], v[72:75]
	v_mfma_f32_16x16x32_bf16 v[68:71], v[210:213], v[242:245], v[68:71]
	s_barrier
	s_add_i32 s0, s0, s90
	v_lshl_add_u64 v[152:153], v[164:165], 0, s[84:85]
	s_mov_b32 m0, s0
	ds_read_b128 v[214:217], v167 offset:49152
	ds_read_b128 v[218:221], v167 offset:50176
	ds_read_b128 v[222:225], v167 offset:51200
	ds_read_b128 v[226:229], v167 offset:52224
	ds_read_b128 v[230:233], v167 offset:53248
	ds_read_b128 v[234:237], v167 offset:54272
	ds_read_b128 v[238:241], v167 offset:55296
	ds_read_b128 v[242:245], v167 offset:56320
	global_load_lds_dwordx4 v[152:153], off
	s_add_i32 m0, s0, 0x2000
	s_add_u32 s10, s10, 0x40080
	v_lshl_add_u64 v[152:153], v[246:247], 0, s[84:85]
	s_addc_u32 s11, s11, 0
	s_add_i32 s0, s1, s90
	global_load_lds_dwordx4 v[152:153], off
	v_lshl_add_u64 v[152:153], s[10:11], 0, v[0:1]
	s_mov_b32 m0, s0
	s_nop 0
	global_load_lds_dwordx4 v[152:153], off
	v_lshl_add_u64 v[152:153], s[10:11], 0, v[132:133]
	s_add_i32 m0, s0, 0x2000
	s_nop 0
	global_load_lds_dwordx4 v[152:153], off
	v_lshl_add_u64 v[152:153], v[248:249], 0, s[84:85]
	s_mov_b32 m0, s94
	s_nop 0
	global_load_lds_dwordx4 v[152:153], off
	v_lshl_add_u64 v[152:153], v[250:251], 0, s[84:85]
	s_mov_b32 m0, s70
	s_nop 0
	global_load_lds_dwordx4 v[152:153], off
	s_waitcnt vmcnt(8)
	s_waitcnt lgkmcnt(0)
	s_barrier
	s_waitcnt lgkmcnt(0)
	v_mfma_f32_16x16x32_bf16 v[64:67], v[168:171], v[214:217], v[64:67]
	v_mfma_f32_16x16x32_bf16 v[60:63], v[190:193], v[214:217], v[60:63]
	v_mfma_f32_16x16x32_bf16 v[52:55], v[168:171], v[222:225], v[52:55]
	v_mfma_f32_16x16x32_bf16 v[44:47], v[190:193], v[222:225], v[44:47]
	v_mfma_f32_16x16x32_bf16 v[36:39], v[168:171], v[230:233], v[36:39]
	v_mfma_f32_16x16x32_bf16 v[28:31], v[190:193], v[230:233], v[28:31]
	v_mfma_f32_16x16x32_bf16 v[20:23], v[168:171], v[238:241], v[20:23]
	v_mfma_f32_16x16x32_bf16 v[12:15], v[190:193], v[238:241], v[12:15]
	v_mfma_f32_16x16x32_bf16 v[64:67], v[172:175], v[218:221], v[64:67]
	v_mfma_f32_16x16x32_bf16 v[60:63], v[194:197], v[218:221], v[60:63]
	v_mfma_f32_16x16x32_bf16 v[52:55], v[172:175], v[226:229], v[52:55]
	v_mfma_f32_16x16x32_bf16 v[44:47], v[194:197], v[226:229], v[44:47]
	v_mfma_f32_16x16x32_bf16 v[36:39], v[172:175], v[234:237], v[36:39]
	v_mfma_f32_16x16x32_bf16 v[28:31], v[194:197], v[234:237], v[28:31]
	v_mfma_f32_16x16x32_bf16 v[20:23], v[172:175], v[242:245], v[20:23]
	v_mfma_f32_16x16x32_bf16 v[12:15], v[194:197], v[242:245], v[12:15]
	v_mfma_f32_16x16x32_bf16 v[56:59], v[198:201], v[214:217], v[56:59]
	v_mfma_f32_16x16x32_bf16 v[48:51], v[206:209], v[214:217], v[48:51]
	v_mfma_f32_16x16x32_bf16 v[40:43], v[198:201], v[222:225], v[40:43]
	v_mfma_f32_16x16x32_bf16 v[32:35], v[206:209], v[222:225], v[32:35]
	v_mfma_f32_16x16x32_bf16 v[24:27], v[198:201], v[230:233], v[24:27]
	v_mfma_f32_16x16x32_bf16 v[16:19], v[206:209], v[230:233], v[16:19]
	v_mfma_f32_16x16x32_bf16 v[8:11], v[198:201], v[238:241], v[8:11]
	v_mfma_f32_16x16x32_bf16 v[4:7], v[206:209], v[238:241], v[4:7]
	v_mfma_f32_16x16x32_bf16 v[56:59], v[202:205], v[218:221], v[56:59]
	v_mfma_f32_16x16x32_bf16 v[48:51], v[210:213], v[218:221], v[48:51]
	v_mfma_f32_16x16x32_bf16 v[40:43], v[202:205], v[226:229], v[40:43]
	v_mfma_f32_16x16x32_bf16 v[32:35], v[210:213], v[226:229], v[32:35]
	v_mfma_f32_16x16x32_bf16 v[24:27], v[202:205], v[234:237], v[24:27]
	v_mfma_f32_16x16x32_bf16 v[16:19], v[210:213], v[234:237], v[16:19]
	v_mfma_f32_16x16x32_bf16 v[8:11], v[202:205], v[242:245], v[8:11]
	v_mfma_f32_16x16x32_bf16 v[4:7], v[210:213], v[242:245], v[4:7]
	s_barrier
	s_add_i32 s77, s77, 2
	s_add_u32 s24, s24, 0x100
	s_addc_u32 s27, s27, 0
	s_add_u32 vcc_lo, vcc_lo, 0x100
	s_addc_u32 vcc_hi, vcc_hi, 0
	s_cmp_gt_u32 s77, 13
	s_cbranch_scc0 .LBB0_766
	s_and_b64 vcc, exec, s[6:7]
	s_cbranch_vccz .LBB0_777
	s_barrier
	v_lshl_or_b32 v164, s14, 8, v166
	v_ashrrev_i32_e32 v165, 31, v164
	v_lshlrev_b64 v[190:191], 2, v[164:165]
	v_lshl_add_u64 v[190:191], s[2:3], 0, v[190:191]
	global_load_dwordx4 v[192:195], v[190:191], off
	global_load_dwordx4 v[196:199], v[190:191], off offset:64
	global_load_dwordx4 v[200:203], v[190:191], off offset:512
	global_load_dwordx4 v[204:207], v[190:191], off offset:576
	s_waitcnt vmcnt(0)
	s_and_saveexec_b64 s[10:11], s[38:39]
	s_cbranch_execnz .LBB0_778
